# NA loop counted waits: wait only for a block's K fragments before QK^T (vmcnt 12) and for its V fragments right before the PV MFMAs (vmcnt 8), on top of v42
# baseline (speedup 1.0000x reference)
.Lna_top_done:
	s_waitcnt vmcnt(12)
	v_mfma_f32_16x16x32_bf16 v[148:151], v[96:99], v[36:39], 0
	v_mfma_f32_16x16x32_bf16 v[152:155], v[100:103], v[36:39], 0
	v_mfma_f32_16x16x32_bf16 v[148:151], v[104:107], v[48:51], v[148:151]
	v_mfma_f32_16x16x32_bf16 v[152:155], v[108:111], v[48:51], v[152:155]
	s_cmp_gt_u32 s12, 3
	s_cbranch_scc0 .Lna_nowin_c1
	ds_read2_b32 v[156:157], v240 offset0:0 offset1:1
	ds_read2_b32 v[158:159], v240 offset0:2 offset1:3
	ds_read2_b32 v[160:161], v240 offset0:4 offset1:5
	ds_read2_b32 v[162:163], v240 offset0:6 offset1:7
	s_nop 3
	s_waitcnt lgkmcnt(0)
	v_add_u32_e32 v3, 0, v128
	v_add_f32_e32 v179, v148, v156
	v_cmp_gt_u32_e32 vcc, 16, v3
	v_add_u32_e32 v172, 1, v128
	v_add_f32_e32 v235, v149, v157
	v_cndmask_b32_e32 v148, v243, v179, vcc
	v_cmp_gt_u32_e32 vcc, 16, v172
	v_add_u32_e32 v3, 2, v128
	v_add_f32_e32 v179, v150, v158
	v_cndmask_b32_e32 v149, v243, v235, vcc
	v_cmp_gt_u32_e32 vcc, 16, v3
	v_add_u32_e32 v172, 3, v128
	v_add_f32_e32 v235, v151, v159
	v_cndmask_b32_e32 v150, v243, v179, vcc
	v_cmp_gt_u32_e32 vcc, 16, v172
	v_add_u32_e32 v3, 4, v128
	v_add_f32_e32 v179, v152, v160
	v_cndmask_b32_e32 v151, v243, v235, vcc
	v_cmp_gt_u32_e32 vcc, 16, v3
	v_add_u32_e32 v172, 5, v128
	v_add_f32_e32 v235, v153, v161
	v_cndmask_b32_e32 v152, v243, v179, vcc
	v_cmp_gt_u32_e32 vcc, 16, v172
	v_add_u32_e32 v3, 6, v128
	v_add_f32_e32 v179, v154, v162
	v_cndmask_b32_e32 v153, v243, v235, vcc
	v_cmp_gt_u32_e32 vcc, 16, v3
	v_add_u32_e32 v172, 7, v128
	v_add_f32_e32 v235, v155, v163
	v_cndmask_b32_e32 v154, v243, v179, vcc
	v_cmp_gt_u32_e32 vcc, 16, v172
	s_nop 1
	v_cndmask_b32_e32 v155, v243, v235, vcc
	s_branch .Lna_sm_c1

.Lna_nors_c1:
	s_waitcnt vmcnt(8)
	s_nop 1
	v_mfma_f32_16x16x32_bf16 v[144:147], v[68:71], v[168:171], v[144:147]
	v_mfma_f32_16x16x32_bf16 v[132:135], v[76:79], v[168:171], v[132:135]
	v_mfma_f32_16x16x32_bf16 v[136:139], v[64:67], v[168:171], v[136:139]
	v_mfma_f32_16x16x32_bf16 v[140:143], v[72:75], v[168:171], v[140:143]
	s_cmp_gt_u32 s12, 3
	s_cselect_b32 s14, s13, 0
	s_cmp_lg_u32 s14, 0
	s_cbranch_scc1 .Lna_skip_c2
	v_mfma_f32_16x16x32_bf16 v[148:151], v[96:99], v[44:47], 0
	v_mfma_f32_16x16x32_bf16 v[152:155], v[100:103], v[44:47], 0
	v_mfma_f32_16x16x32_bf16 v[148:151], v[104:107], v[40:43], v[148:151]
	v_mfma_f32_16x16x32_bf16 v[152:155], v[108:111], v[40:43], v[152:155]
	s_cmp_gt_u32 s12, 3
	s_cbranch_scc0 .Lna_nowin_c2
	ds_read2_b32 v[156:157], v241 offset0:0 offset1:1
	ds_read2_b32 v[158:159], v241 offset0:2 offset1:3
	ds_read2_b32 v[160:161], v241 offset0:4 offset1:5
	ds_read2_b32 v[162:163], v241 offset0:6 offset1:7
	s_nop 3
	s_waitcnt lgkmcnt(0)
	v_add_u32_e32 v3, 0, v130
	v_add_f32_e32 v179, v148, v156
	v_cmp_gt_u32_e32 vcc, 16, v3
	v_add_u32_e32 v172, 1, v130
	v_add_f32_e32 v235, v149, v157
	v_cndmask_b32_e32 v148, v243, v179, vcc
	v_cmp_gt_u32_e32 vcc, 16, v172
	v_add_u32_e32 v3, 2, v130
	v_add_f32_e32 v179, v150, v158
	v_cndmask_b32_e32 v149, v243, v235, vcc
	v_cmp_gt_u32_e32 vcc, 16, v3
	v_add_u32_e32 v172, 3, v130
	v_add_f32_e32 v235, v151, v159
	v_cndmask_b32_e32 v150, v243, v179, vcc
	v_cmp_gt_u32_e32 vcc, 16, v172
	v_add_u32_e32 v3, 4, v130
	v_add_f32_e32 v179, v152, v160
	v_cndmask_b32_e32 v151, v243, v235, vcc
	v_cmp_gt_u32_e32 vcc, 16, v3
	v_add_u32_e32 v172, 5, v130
	v_add_f32_e32 v235, v153, v161
	v_cndmask_b32_e32 v152, v243, v179, vcc
	v_cmp_gt_u32_e32 vcc, 16, v172
	v_add_u32_e32 v3, 6, v130
	v_add_f32_e32 v179, v154, v162
	v_cndmask_b32_e32 v153, v243, v235, vcc
	v_cmp_gt_u32_e32 vcc, 16, v3
	v_add_u32_e32 v172, 7, v130
	v_add_f32_e32 v235, v155, v163
	v_cndmask_b32_e32 v154, v243, v179, vcc
	v_cmp_gt_u32_e32 vcc, 16, v172
	s_nop 1
	v_cndmask_b32_e32 v155, v243, v235, vcc
	s_branch .Lna_sm_c2

.Lna_nors_c2:
	s_waitcnt vmcnt(8)
	s_nop 1
	v_mfma_f32_16x16x32_bf16 v[52:55], v[68:71], v[168:171], v[52:55]
	v_mfma_f32_16x16x32_bf16 v[56:59], v[76:79], v[168:171], v[56:59]
	v_mfma_f32_16x16x32_bf16 v[60:63], v[64:67], v[168:171], v[60:63]
	v_mfma_f32_16x16x32_bf16 v[164:167], v[72:75], v[168:171], v[164:167]

.Lna_mid_skip:
	s_waitcnt vmcnt(12)
	s_cmp_gt_u32 s12, 3
	s_cselect_b32 s14, 1, 0
	s_cmp_eq_u32 s13, 0
	s_cselect_b32 s0, 1, 0
	s_and_b32 s14, s14, s0
	s_cmp_lg_u32 s14, 0
	s_cbranch_scc1 .Lna_skip_c3
	v_mfma_f32_16x16x32_bf16 v[148:151], v[112:115], v[36:39], 0
	v_mfma_f32_16x16x32_bf16 v[152:155], v[116:119], v[36:39], 0
	v_mfma_f32_16x16x32_bf16 v[148:151], v[120:123], v[48:51], v[148:151]
	v_mfma_f32_16x16x32_bf16 v[152:155], v[124:127], v[48:51], v[152:155]
	s_cmp_gt_u32 s12, 3
	s_cbranch_scc0 .Lna_nowin_c3
	ds_read2_b32 v[156:157], v240 offset0:32 offset1:33
	ds_read2_b32 v[158:159], v240 offset0:34 offset1:35
	ds_read2_b32 v[160:161], v240 offset0:36 offset1:37
	ds_read2_b32 v[162:163], v240 offset0:38 offset1:39
	s_nop 3
	s_waitcnt lgkmcnt(0)
	v_add_u32_e32 v3, 0, v129
	v_add_f32_e32 v179, v148, v156
	v_cmp_gt_u32_e32 vcc, 16, v3
	v_add_u32_e32 v172, 1, v129
	v_add_f32_e32 v235, v149, v157
	v_cndmask_b32_e32 v148, v243, v179, vcc
	v_cmp_gt_u32_e32 vcc, 16, v172
	v_add_u32_e32 v3, 2, v129
	v_add_f32_e32 v179, v150, v158
	v_cndmask_b32_e32 v149, v243, v235, vcc
	v_cmp_gt_u32_e32 vcc, 16, v3
	v_add_u32_e32 v172, 3, v129
	v_add_f32_e32 v235, v151, v159
	v_cndmask_b32_e32 v150, v243, v179, vcc
	v_cmp_gt_u32_e32 vcc, 16, v172
	v_add_u32_e32 v3, 4, v129
	v_add_f32_e32 v179, v152, v160
	v_cndmask_b32_e32 v151, v243, v235, vcc
	v_cmp_gt_u32_e32 vcc, 16, v3
	v_add_u32_e32 v172, 5, v129
	v_add_f32_e32 v235, v153, v161
	v_cndmask_b32_e32 v152, v243, v179, vcc
	v_cmp_gt_u32_e32 vcc, 16, v172
	v_add_u32_e32 v3, 6, v129
	v_add_f32_e32 v179, v154, v162
	v_cndmask_b32_e32 v153, v243, v235, vcc
	v_cmp_gt_u32_e32 vcc, 16, v3
	v_add_u32_e32 v172, 7, v129
	v_add_f32_e32 v235, v155, v163
	v_cndmask_b32_e32 v154, v243, v179, vcc
	v_cmp_gt_u32_e32 vcc, 16, v172
	s_nop 1
	v_cndmask_b32_e32 v155, v243, v235, vcc
	s_branch .Lna_sm_c3

.Lna_nors_c3:
	s_waitcnt vmcnt(8)
	s_nop 1
	v_mfma_f32_16x16x32_bf16 v[144:147], v[80:83], v[168:171], v[144:147]
	v_mfma_f32_16x16x32_bf16 v[132:135], v[84:87], v[168:171], v[132:135]
	v_mfma_f32_16x16x32_bf16 v[136:139], v[88:91], v[168:171], v[136:139]
	v_mfma_f32_16x16x32_bf16 v[140:143], v[92:95], v[168:171], v[140:143]

.Lna_nors_c4:
	s_waitcnt vmcnt(8)
	s_nop 1
	v_mfma_f32_16x16x32_bf16 v[52:55], v[80:83], v[168:171], v[52:55]
	v_mfma_f32_16x16x32_bf16 v[56:59], v[84:87], v[168:171], v[56:59]
	v_mfma_f32_16x16x32_bf16 v[60:63], v[88:91], v[168:171], v[60:63]
	v_mfma_f32_16x16x32_bf16 v[164:167], v[92:95], v[168:171], v[164:167]
	v_add_u32_e32 v240, 0x7c, v240
	v_add_u32_e32 v241, 0x7c, v241
	s_add_i32 s12, s12, 1
	v_readlane_b32 s14, v252, 23
	s_nop 3
	s_cmp_lt_u32 s12, s14
	s_cbranch_scc1 .Lna_loop
	s_waitcnt vmcnt(0)
	v_readlane_b32 s90, v254, 8
	v_readlane_b32 s91, v254, 9
	s_mov_b32 s96, 0x1e000
	s_nop 7
